# bundle3: waves 0-3 keep first Wp product tile before MFMA block inverses, waves 4-7 take one extra tile (rebalance of bundle2)
# baseline (speedup 1.0000x reference)
.LBB0_385:
	s_waitcnt lgkmcnt(0)
	s_barrier
	s_waitcnt lgkmcnt(0)
	v_readfirstlane_b32 s26, v0
	s_lshr_b32 s26, s26, 6
	ds_read_b128 v[66:69], v224 offset:16384
	ds_read_b128 v[70:73], v225
	v_cndmask_b32_e64 v26, 0, 1, s[4:5]
	v_cmp_ne_u32_e64 s[52:53], 1, v26
	s_waitcnt lgkmcnt(0)
	v_mfma_f32_16x16x32_bf16 v[66:69], v[66:69], v[70:73], 0
	s_andn2_b64 vcc, exec, s[4:5]
	s_cbranch_vccnz .LBB0_387
	ds_read_b128 v[70:73], v224 offset:16448
	ds_read_b128 v[74:77], v225 offset:64
	s_waitcnt lgkmcnt(0)
	v_mfma_f32_16x16x32_bf16 v[66:69], v[70:73], v[74:77], v[66:69]
.LBB0_387:
	v_add_u32_e32 v26, 0x8000, v202
	s_nop 6
	ds_write2_b32 v26, v66, v67 offset1:72
	ds_write2_b32 v26, v68, v69 offset0:144 offset1:216
	s_cmp_lt_u32 s26, 4
	s_cbranch_scc1 .Lp5_skip
	ds_read_b128 v[66:69], v224 offset:16384
	ds_read_b128 v[70:73], v226
	s_and_b64 vcc, exec, s[52:53]
	s_waitcnt lgkmcnt(0)
	v_mfma_f32_16x16x32_bf16 v[66:69], v[66:69], v[70:73], 0
	s_cbranch_vccnz .LBB0_389
	ds_read_b128 v[70:73], v224 offset:16448
	ds_read_b128 v[74:77], v226 offset:64
	s_waitcnt lgkmcnt(0)
	v_mfma_f32_16x16x32_bf16 v[66:69], v[70:73], v[74:77], v[66:69]
.LBB0_389:
	s_andn2_b64 vcc, exec, s[8:9]
	s_nop 6
	ds_write2_b32 v26, v66, v67 offset0:16 offset1:88
	ds_write2_b32 v26, v68, v69 offset0:160 offset1:232
	v_add_u32_e32 v27, 0xffffec00, v224
	v_add_u32_e32 v28, 0xffffdc00, v26
	ds_read_b128 v[66:69], v27 offset:16384
	ds_read_b128 v[70:73], v226
	s_waitcnt lgkmcnt(0)
	v_mfma_f32_16x16x32_bf16 v[66:69], v[66:69], v[70:73], 0
	s_nop 7
	ds_write2_b32 v28, v66, v67 offset0:16 offset1:88
	ds_write2_b32 v28, v68, v69 offset0:160 offset1:232
